# nt hint also on the read-once x/delta row loads of P5 (gain vector loads unchanged)
# speedup vs baseline: 1.0124x; 1.0004x over previous
; __device__ __forceinline__ float bf_lo(unsigned w) { return __uint_as_float(w << 16); }
; __device__ __forceinline__ float bf_hi(unsigned w) { return __uint_as_float(w & 0xffff0000u); }
; template <int NR>
; __device__ __forceinline__ void p5_rows(const Params& p, const bf16_t* __restrict__ DL, int r, int nw, int lane) {
;     ...
;     for (int k = 0; k < NR; ++k) { const int row = r + k * nw; const float* x = row < TP ? p.xp + (size_t)row * D : p.xs + (size_t)(row - TP) * D;
; #pragma unroll
;         for (int i = 0; i < 4; ++i) { v[k][2 * i] = *(const f32x4*)(x + (i * 64 + lane) * 8); v[k][2 * i + 1] = *(const f32x4*)(x + (i * 64 + lane) * 8 + 4);
;             d[k][i] = *(const u32x4*)(DL + (size_t)row * LDP + (i * 64 + lane) * 8); } }
; #pragma unroll
;     for (int k = 0; k < NR; ++k) { const int row = r + k * nw; float ss = 0.f;
; #pragma unroll
;         for (int i = 0; i < 4; ++i) { const u32x4 w = d[k][i];
;             v[k][2 * i] += (f32x4){bf_lo(w.x), bf_hi(w.x), bf_lo(w.y), bf_hi(w.y)}; v[k][2 * i + 1] += (f32x4){bf_lo(w.z), bf_hi(w.z), bf_lo(w.w), bf_hi(w.w)}; }
; #pragma unroll
;         for (int i = 0; i < 8; ++i) ss += (v[k][i][0] * v[k][i][0] + v[k][i][1] * v[k][i][1]) + (v[k][i][2] * v[k][i][2] + v[k][i][3] * v[k][i][3]);
.LBB0_1190:
	s_or_b64 exec, exec, s[10:11]
	v_mad_u64_u32 v[4:5], s[10:11], v6, s13, v[82:83]
	v_mov_b32_e32 v6, v5
	v_lshl_add_u64 v[2:3], v[0:1], 0, v[74:75]
	v_mad_u64_u32 v[6:7], s[10:11], v7, s13, v[6:7]
	global_load_dwordx4 v[106:109], v[2:3], off offset:16 nt
	global_load_dwordx4 v[110:113], v[2:3], off nt
	v_mov_b32_e32 v5, v6
	global_load_dwordx4 v[114:117], v[2:3], off offset:2064 nt
	global_load_dwordx4 v[118:121], v[2:3], off offset:2048 nt
	global_load_dwordx4 v[122:125], v[4:5], off nt
	global_load_dwordx4 v[126:129], v[4:5], off offset:1024 nt
	v_mov_b32_e32 v87, v75
	v_mov_b32_e32 v89, v75
	v_lshl_add_u64 v[2:3], v[0:1], 0, v[86:87]
	v_lshl_add_u64 v[6:7], v[0:1], 0, v[88:89]
	global_load_dwordx4 v[12:15], v[2:3], off offset:16 nt
	global_load_dwordx4 v[16:19], v[2:3], off nt
	s_nop 0
	global_load_dwordx4 v[0:3], v[6:7], off offset:16 nt
	global_load_dwordx4 v[8:11], v[6:7], off nt
	global_load_dwordx4 v[130:133], v[4:5], off offset:2048 nt
	s_nop 0
	global_load_dwordx4 v[4:7], v[4:5], off offset:3072 nt
	s_waitcnt vmcnt(19)
	v_lshlrev_b32_e32 v134, 16, v64
	v_and_b32_e32 v135, 0xffff0000, v64
	v_lshlrev_b32_e32 v64, 16, v65
	v_and_b32_e32 v65, 0xffff0000, v65
	v_pk_add_f32 v[62:63], v[62:63], v[64:65]
	v_lshlrev_b32_e32 v64, 16, v66
	v_and_b32_e32 v65, 0xffff0000, v66
	v_lshlrev_b32_e32 v66, 16, v67
	v_and_b32_e32 v67, 0xffff0000, v67
	v_pk_add_f32 v[58:59], v[58:59], v[66:67]
	v_pk_add_f32 v[56:57], v[56:57], v[64:65]
	s_waitcnt vmcnt(18)
	v_lshlrev_b32_e32 v64, 16, v48
	v_and_b32_e32 v65, 0xffff0000, v48
	v_lshlrev_b32_e32 v66, 16, v49
	v_and_b32_e32 v67, 0xffff0000, v49
	v_pk_add_f32 v[48:49], v[52:53], v[64:65]
	v_pk_add_f32 v[52:53], v[54:55], v[66:67]
	v_lshlrev_b32_e32 v54, 16, v50
	v_and_b32_e32 v55, 0xffff0000, v50
	v_lshlrev_b32_e32 v50, 16, v51
	v_and_b32_e32 v51, 0xffff0000, v51
	v_pk_add_f32 v[46:47], v[46:47], v[50:51]
	s_waitcnt vmcnt(13)
	v_lshlrev_b32_e32 v50, 16, v40
	v_and_b32_e32 v51, 0xffff0000, v40
	v_lshlrev_b32_e32 v40, 16, v41
	v_and_b32_e32 v41, 0xffff0000, v41
	v_pk_add_f32 v[38:39], v[38:39], v[40:41]
	v_lshlrev_b32_e32 v40, 16, v42
	v_and_b32_e32 v41, 0xffff0000, v42
	v_pk_add_f32 v[32:33], v[32:33], v[40:41]
	s_waitcnt vmcnt(12)
	v_lshlrev_b32_e32 v40, 16, v24
	v_and_b32_e32 v41, 0xffff0000, v24
	v_lshlrev_b32_e32 v24, 16, v25
	v_and_b32_e32 v25, 0xffff0000, v25
	v_pk_add_f32 v[60:61], v[60:61], v[134:135]
	v_pk_add_f32 v[24:25], v[30:31], v[24:25]
	v_lshlrev_b32_e32 v30, 16, v26
	v_and_b32_e32 v31, 0xffff0000, v26
	v_lshlrev_b32_e32 v26, 16, v27
	v_and_b32_e32 v27, 0xffff0000, v27
	v_pk_add_f32 v[20:21], v[20:21], v[30:31]
	v_mov_b32_e32 v30, v61
	v_mov_b32_e32 v31, v57
	v_pk_add_f32 v[28:29], v[28:29], v[40:41]
	v_pk_add_f32 v[22:23], v[22:23], v[26:27]
	v_mov_b32_e32 v26, v60
	v_mov_b32_e32 v27, v56
	v_pk_mul_f32 v[30:31], v[30:31], v[30:31]
	v_mov_b32_e32 v40, v63
	v_mov_b32_e32 v41, v59
	v_pk_fma_f32 v[26:27], v[26:27], v[26:27], v[30:31]
	v_mov_b32_e32 v30, v62
	v_mov_b32_e32 v31, v58
	v_pk_mul_f32 v[40:41], v[40:41], v[40:41]
	v_lshlrev_b32_e32 v42, 16, v43
	v_pk_fma_f32 v[30:31], v[30:31], v[30:31], v[40:41]
	v_and_b32_e32 v43, 0xffff0000, v43
	v_pk_add_f32 v[26:27], v[26:27], v[30:31]
	v_pk_mul_f32 v[30:31], v[52:53], v[52:53]
	v_pk_mul_f32 v[40:41], v[48:49], v[48:49]
	v_pk_add_f32 v[44:45], v[44:45], v[54:55]
	v_pk_add_f32 v[34:35], v[34:35], v[42:43]
	v_pk_mov_b32 v[42:43], v[40:41], v[30:31] op_sel:[1,0]
	v_mov_b32_e32 v41, v31
	v_pk_add_f32 v[36:37], v[36:37], v[50:51]
	v_pk_add_f32 v[30:31], v[42:43], v[40:41]
	v_mul_f32_e32 v40, v45, v45
	v_mul_f32_e32 v42, v36, v36
	v_pk_fma_f32 v[40:41], v[44:45], v[44:45], v[40:41] op_sel_hi:[1,1,0]
	v_mul_f32_e32 v50, v37, v37
	v_mov_b32_e32 v41, v42
	v_mul_f32_e32 v42, v47, v47
	v_mul_f32_e32 v51, v38, v38
	v_mul_f32_e32 v54, v39, v39
	v_pk_fma_f32 v[42:43], v[46:47], v[46:47], v[42:43] op_sel_hi:[1,1,0]
	v_pk_add_f32 v[26:27], v[26:27], v[26:27] op_sel:[0,1] op_sel_hi:[1,0]
	v_pk_add_f32 v[30:31], v[30:31], v[30:31] op_sel:[0,1] op_sel_hi:[1,0]
	v_mov_b32_e32 v43, v50
	v_mov_b32_e32 v27, v51
	v_mov_b32_e32 v31, v54
	v_pk_add_f32 v[40:41], v[40:41], v[42:43]
	v_pk_add_f32 v[26:27], v[26:27], v[30:31]
	global_load_dwordx4 v[134:137], v[76:77], off offset:16
	global_load_dwordx4 v[138:141], v[76:77], off
	v_pk_add_f32 v[26:27], v[40:41], v[26:27]
	v_pk_mul_f32 v[30:31], v[34:35], v[34:35]
	v_pk_add_f32 v[26:27], v[26:27], v[26:27] op_sel_hi:[0,1]
	v_pk_mul_f32 v[40:41], v[32:33], v[32:33]
	v_mul_f32_e32 v26, v28, v28
	v_pk_mov_b32 v[42:43], v[40:41], v[30:31] op_sel:[1,0]
	v_mov_b32_e32 v41, v31
	v_pk_add_f32 v[30:31], v[42:43], v[40:41]
	v_pk_fma_f32 v[40:41], v[28:29], v[28:29], v[26:27] op_sel_hi:[1,1,0]
	v_mul_f32_e32 v26, v24, v24
	v_pk_add_f32 v[30:31], v[30:31], v[30:31] op_sel_hi:[0,1]
	v_pk_fma_f32 v[42:43], v[24:25], v[24:25], v[26:27] op_sel_hi:[1,1,0]
	v_mul_f32_e32 v30, v20, v20
	v_mul_f32_e32 v26, v21, v21
	v_mul_f32_e32 v40, v22, v22
	v_mul_f32_e32 v42, v23, v23
	v_pk_add_f32 v[26:27], v[30:31], v[26:27]
	v_pk_add_f32 v[30:31], v[40:41], v[42:43]
	s_waitcnt vmcnt(9)
	v_lshlrev_b32_e32 v40, 16, v125
	v_pk_add_f32 v[142:143], v[26:27], v[30:31]
	v_lshlrev_b32_e32 v26, 16, v122
	v_and_b32_e32 v27, 0xffff0000, v122
	v_pk_add_f32 v[42:43], v[110:111], v[26:27]
	v_lshlrev_b32_e32 v26, 16, v124
	v_and_b32_e32 v27, 0xffff0000, v124
	v_pk_add_f32 v[66:67], v[106:107], v[26:27]
	s_waitcnt vmcnt(3)
	v_lshlrev_b32_e32 v106, 16, v130
	v_and_b32_e32 v107, 0xffff0000, v130
	v_pk_add_f32 v[16:17], v[16:17], v[106:107]
	v_lshlrev_b32_e32 v106, 16, v132
	v_and_b32_e32 v107, 0xffff0000, v132
	v_pk_add_f32 v[12:13], v[12:13], v[106:107]
	s_waitcnt vmcnt(2)
; __device__ __forceinline__ float bf_lo(unsigned w) { return __uint_as_float(w << 16); }
; __device__ __forceinline__ float bf_hi(unsigned w) { return __uint_as_float(w & 0xffff0000u); }
; template <int NR>
; __device__ __forceinline__ void p5_rows(const Params& p, const bf16_t* __restrict__ DL, int r, int nw, int lane) {
;     ...
;     for (int k = 0; k < NR; ++k) { const int row = r + k * nw; float ss = 0.f;
; #pragma unroll
;         for (int i = 0; i < 4; ++i) { const u32x4 w = d[k][i];
;             v[k][2 * i] += (f32x4){bf_lo(w.x), bf_hi(w.x), bf_lo(w.y), bf_hi(w.y)}; v[k][2 * i + 1] += (f32x4){bf_lo(w.z), bf_hi(w.z), bf_lo(w.w), bf_hi(w.w)}; }
; #pragma unroll
;         for (int i = 0; i < 8; ++i) ss += (v[k][i][0] * v[k][i][0] + v[k][i][1] * v[k][i][1]) + (v[k][i][2] * v[k][i][2] + v[k][i][3] * v[k][i][3]);
; #pragma unroll
;         for (int o = 32; o >= 1; o >>= 1) ss += __shfl_xor(ss, o);
;         const float rs = rsqrtf(ss * (1.0f / D) + EPS);
;         float* y = p.out + O_Y + (size_t)row * D;
; #pragma unroll
;         for (int i = 0; i < 4; ++i) { const f32x4 g0 = *(const f32x4*)(p.fng + (i * 64 + lane) * 8), g1 = *(const f32x4*)(p.fng + (i * 64 + lane) * 8 + 4);
;             *(f32x4*)(y + (i * 64 + lane) * 8) = v[k][2 * i] * rs * g0; *(f32x4*)(y + (i * 64 + lane) * 8 + 4) = v[k][2 * i + 1] * rs * g1; } }
	v_lshlrev_b32_e32 v106, 16, v4
	v_and_b32_e32 v107, 0xffff0000, v4
	v_lshlrev_b32_e32 v4, 16, v5
	v_and_b32_e32 v5, 0xffff0000, v5
	v_lshlrev_b32_e32 v30, 16, v123
	v_and_b32_e32 v31, 0xffff0000, v123
	v_and_b32_e32 v41, 0xffff0000, v125
	v_pk_add_f32 v[4:5], v[10:11], v[4:5]
	v_lshlrev_b32_e32 v10, 16, v6
	v_and_b32_e32 v11, 0xffff0000, v6
	v_pk_add_f32 v[30:31], v[112:113], v[30:31]
	v_pk_add_f32 v[64:65], v[108:109], v[40:41]
	v_lshlrev_b32_e32 v6, 16, v7
	v_and_b32_e32 v7, 0xffff0000, v7
	v_pk_add_f32 v[0:1], v[0:1], v[10:11]
	v_mov_b32_e32 v10, v43
	v_mov_b32_e32 v11, v67
	v_pk_add_f32 v[8:9], v[8:9], v[106:107]
	v_pk_add_f32 v[2:3], v[2:3], v[6:7]
	v_mov_b32_e32 v6, v42
	v_mov_b32_e32 v7, v66
	v_pk_mul_f32 v[10:11], v[10:11], v[10:11]
	v_mov_b32_e32 v106, v31
	v_mov_b32_e32 v107, v65
	v_lshlrev_b32_e32 v26, 16, v126
	v_and_b32_e32 v27, 0xffff0000, v126
	v_lshlrev_b32_e32 v40, 16, v127
	v_and_b32_e32 v41, 0xffff0000, v127
	v_pk_fma_f32 v[6:7], v[6:7], v[6:7], v[10:11]
	v_mov_b32_e32 v10, v30
	v_mov_b32_e32 v11, v64
	v_pk_mul_f32 v[106:107], v[106:107], v[106:107]
	v_pk_add_f32 v[26:27], v[118:119], v[26:27]
	v_pk_add_f32 v[50:51], v[120:121], v[40:41]
	v_lshlrev_b32_e32 v108, 16, v131
	v_and_b32_e32 v109, 0xffff0000, v131
	v_pk_fma_f32 v[10:11], v[10:11], v[10:11], v[106:107]
	v_lshlrev_b32_e32 v54, 16, v128
	v_and_b32_e32 v55, 0xffff0000, v128
	v_lshlrev_b32_e32 v40, 16, v129
	v_and_b32_e32 v41, 0xffff0000, v129
	v_pk_add_f32 v[18:19], v[18:19], v[108:109]
	v_lshlrev_b32_e32 v108, 16, v133
	v_and_b32_e32 v109, 0xffff0000, v133
	v_pk_add_f32 v[6:7], v[6:7], v[10:11]
	v_pk_mul_f32 v[10:11], v[50:51], v[50:51]
	v_pk_mul_f32 v[106:107], v[26:27], v[26:27]
	v_pk_add_f32 v[40:41], v[116:117], v[40:41]
	v_pk_add_f32 v[54:55], v[114:115], v[54:55]
	v_pk_add_f32 v[14:15], v[14:15], v[108:109]
	v_pk_mov_b32 v[108:109], v[106:107], v[10:11] op_sel:[1,0]
	v_mov_b32_e32 v107, v11
	v_pk_add_f32 v[10:11], v[108:109], v[106:107]
	v_mul_f32_e32 v106, v55, v55
	v_mul_f32_e32 v108, v41, v41
	v_mul_f32_e32 v69, v16, v16
	v_mul_f32_e32 v73, v17, v17
	v_mul_f32_e32 v110, v18, v18
	v_mul_f32_e32 v111, v19, v19
	v_pk_fma_f32 v[106:107], v[54:55], v[54:55], v[106:107] op_sel_hi:[1,1,0]
	v_pk_fma_f32 v[108:109], v[40:41], v[40:41], v[108:109] op_sel_hi:[1,1,0]
	v_pk_add_f32 v[6:7], v[6:7], v[6:7] op_sel:[0,1] op_sel_hi:[1,0]
	v_pk_add_f32 v[10:11], v[10:11], v[10:11] op_sel:[0,1] op_sel_hi:[1,0]
	v_mov_b32_e32 v107, v69
	v_mov_b32_e32 v109, v73
	v_mov_b32_e32 v7, v110
	v_mov_b32_e32 v11, v111
	v_pk_add_f32 v[106:107], v[106:107], v[108:109]
	v_pk_add_f32 v[6:7], v[6:7], v[10:11]
	v_pk_mul_f32 v[10:11], v[14:15], v[14:15]
	v_pk_add_f32 v[6:7], v[106:107], v[6:7]
	v_pk_mul_f32 v[106:107], v[12:13], v[12:13]
	v_pk_add_f32 v[6:7], v[6:7], v[6:7] op_sel_hi:[0,1]
	v_pk_mov_b32 v[108:109], v[106:107], v[10:11] op_sel:[1,0]
	v_mov_b32_e32 v107, v11
	v_mul_f32_e32 v6, v8, v8
	v_pk_add_f32 v[10:11], v[108:109], v[106:107]
	v_pk_fma_f32 v[106:107], v[8:9], v[8:9], v[6:7] op_sel_hi:[1,1,0]
	v_mul_f32_e32 v6, v4, v4
	v_pk_add_f32 v[10:11], v[10:11], v[10:11] op_sel_hi:[0,1]
	v_pk_fma_f32 v[108:109], v[4:5], v[4:5], v[6:7] op_sel_hi:[1,1,0]
	v_mul_f32_e32 v10, v0, v0
	v_mul_f32_e32 v6, v1, v1
	v_mul_f32_e32 v106, v2, v2
	v_mul_f32_e32 v108, v3, v3
	v_pk_add_f32 v[6:7], v[10:11], v[6:7]
	v_pk_add_f32 v[10:11], v[106:107], v[108:109]
	v_lshl_add_u64 v[70:71], v[70:71], 0, s[2:3]
	v_pk_add_f32 v[6:7], v[6:7], v[10:11]
	v_mov_b32_e32 v11, v142
	v_mov_b32_e32 v10, v6
	v_mov_b32_e32 v142, v7
	v_pk_add_f32 v[6:7], v[10:11], v[142:143]
	ds_bpermute_b32 v11, v100, v7
	ds_bpermute_b32 v10, v100, v6
	v_lshl_add_u64 v[84:85], v[84:85], 0, s[4:5]
	s_waitcnt lgkmcnt(0)
	v_pk_add_f32 v[6:7], v[6:7], v[10:11]
	ds_bpermute_b32 v11, v101, v7
	ds_bpermute_b32 v10, v101, v6
	s_waitcnt lgkmcnt(0)
	v_pk_add_f32 v[6:7], v[6:7], v[10:11]
	ds_bpermute_b32 v11, v102, v7
	ds_bpermute_b32 v10, v102, v6
	s_waitcnt lgkmcnt(0)
	v_pk_add_f32 v[6:7], v[6:7], v[10:11]
	ds_bpermute_b32 v11, v103, v7
	ds_bpermute_b32 v10, v103, v6
	s_waitcnt lgkmcnt(0)
	v_pk_add_f32 v[6:7], v[6:7], v[10:11]
	ds_bpermute_b32 v11, v104, v7
	ds_bpermute_b32 v10, v104, v6
	s_waitcnt lgkmcnt(0)
	v_pk_add_f32 v[6:7], v[6:7], v[10:11]
	ds_bpermute_b32 v11, v105, v7
	ds_bpermute_b32 v10, v105, v6
	s_waitcnt lgkmcnt(0)
	v_pk_add_f32 v[6:7], v[6:7], v[10:11]
	s_nop 0
	v_pk_fma_f32 v[6:7], v[6:7], s[8:9], v[94:95] op_sel_hi:[1,0,0]
	v_add_u32_e32 v95, s2, v95
	v_mul_f32_e32 v10, 0x4b800000, v7
	v_cmp_gt_f32_e32 vcc, s14, v7
	s_nop 1
	v_cndmask_b32_e32 v7, v7, v10, vcc
	v_rsq_f32_e32 v7, v7
	v_lshlrev_b64 v[10:11], 13, v[98:99]
	v_lshl_add_u64 v[10:11], s[24:25], 0, v[10:11]
	v_lshl_add_u64 v[98:99], v[10:11], 0, v[74:75]
	v_mul_f32_e32 v69, 0x45800000, v7
	v_cndmask_b32_e32 v106, v7, v69, vcc
	v_pk_mul_f32 v[60:61], v[60:61], v[106:107] op_sel_hi:[1,0]
	v_pk_mul_f32 v[62:63], v[62:63], v[106:107] op_sel_hi:[1,0]
	v_pk_mul_f32 v[56:57], v[56:57], v[106:107] op_sel_hi:[1,0]
	v_pk_mul_f32 v[58:59], v[58:59], v[106:107] op_sel_hi:[1,0]
	s_waitcnt vmcnt(0)
	v_pk_mul_f32 v[62:63], v[140:141], v[62:63]
	v_pk_mul_f32 v[60:61], v[138:139], v[60:61]
	v_pk_mul_f32 v[58:59], v[136:137], v[58:59]
	v_pk_mul_f32 v[56:57], v[134:135], v[56:57]
	global_store_dwordx4 v[98:99], v[60:63], off
	global_store_dwordx4 v[98:99], v[56:59], off offset:16
	global_load_dwordx4 v[56:59], v[76:77], off offset:2048
	s_nop 0
	global_load_dwordx4 v[60:63], v[76:77], off offset:2064
	v_pk_mul_f32 v[52:53], v[52:53], v[106:107] op_sel_hi:[1,0]
	v_pk_mul_f32 v[48:49], v[48:49], v[106:107] op_sel_hi:[1,0]
	v_pk_mul_f32 v[46:47], v[46:47], v[106:107] op_sel_hi:[1,0]
	v_pk_mul_f32 v[44:45], v[44:45], v[106:107] op_sel_hi:[1,0]
	v_pk_mul_f32 v[38:39], v[38:39], v[106:107] op_sel_hi:[1,0]
	v_pk_mul_f32 v[36:37], v[36:37], v[106:107] op_sel_hi:[1,0]
	v_pk_mul_f32 v[24:25], v[24:25], v[106:107] op_sel_hi:[1,0]
	v_pk_mul_f32 v[28:29], v[28:29], v[106:107] op_sel_hi:[1,0]
	v_mul_f32_e32 v7, 0x4b800000, v6
	v_cmp_gt_f32_e32 vcc, s14, v6
	s_waitcnt vmcnt(1)
; template <int NR>
; __device__ __forceinline__ void p5_rows(const Params& p, const bf16_t* __restrict__ DL, int r, int nw, int lane) {
;     ...
;     for (int k = 0; k < NR; ++k) { const int row = r + k * nw; const float* x = row < TP ? p.xp + (size_t)row * D : p.xs + (size_t)(row - TP) * D;
; #pragma unroll
;         for (int i = 0; i < 4; ++i) { v[k][2 * i] = *(const f32x4*)(x + (i * 64 + lane) * 8); v[k][2 * i + 1] = *(const f32x4*)(x + (i * 64 + lane) * 8 + 4);
;             d[k][i] = *(const u32x4*)(DL + (size_t)row * LDP + (i * 64 + lane) * 8); } }
;     ...
;         float* y = p.out + O_Y + (size_t)row * D;
; #pragma unroll
;         for (int i = 0; i < 4; ++i) { const f32x4 g0 = *(const f32x4*)(p.fng + (i * 64 + lane) * 8), g1 = *(const f32x4*)(p.fng + (i * 64 + lane) * 8 + 4);
;             *(f32x4*)(y + (i * 64 + lane) * 8) = v[k][2 * i] * rs * g0; *(f32x4*)(y + (i * 64 + lane) * 8 + 4) = v[k][2 * i + 1] * rs * g1; } }
	v_pk_mul_f32 v[56:57], v[56:57], v[48:49]
	v_pk_mul_f32 v[58:59], v[58:59], v[52:53]
	s_waitcnt vmcnt(0)
	v_pk_mul_f32 v[44:45], v[60:61], v[44:45]
	v_pk_mul_f32 v[46:47], v[62:63], v[46:47]
	global_store_dwordx4 v[98:99], v[56:59], off offset:2048
	global_store_dwordx4 v[98:99], v[44:47], off offset:2064
	global_load_dwordx4 v[44:47], v[78:79], off
	s_nop 0
	global_load_dwordx4 v[56:59], v[78:79], off offset:16
	v_lshl_add_u64 v[48:49], v[10:11], 0, v[86:87]
	v_pk_mul_f32 v[52:53], v[34:35], v[106:107] op_sel_hi:[1,0]
	v_pk_mul_f32 v[60:61], v[32:33], v[106:107] op_sel_hi:[1,0]
	v_lshl_add_u64 v[10:11], v[10:11], 0, v[88:89]
	v_cndmask_b32_e32 v6, v6, v7, vcc
	s_waitcnt vmcnt(1)
	v_pk_mul_f32 v[32:33], v[44:45], v[36:37]
	v_pk_mul_f32 v[34:35], v[46:47], v[38:39]
	s_waitcnt vmcnt(0)
	v_pk_mul_f32 v[36:37], v[56:57], v[60:61]
	v_pk_mul_f32 v[38:39], v[58:59], v[52:53]
	global_store_dwordx4 v[48:49], v[32:35], off
	global_store_dwordx4 v[48:49], v[36:39], off offset:16
	global_load_dwordx4 v[32:35], v[80:81], off
	s_nop 0
	global_load_dwordx4 v[36:39], v[80:81], off offset:16
	v_pk_mul_f32 v[44:45], v[22:23], v[106:107] op_sel_hi:[1,0]
	v_pk_mul_f32 v[46:47], v[20:21], v[106:107] op_sel_hi:[1,0]
	s_waitcnt vmcnt(1)
	v_pk_mul_f32 v[20:21], v[28:29], v[32:33]
	v_pk_mul_f32 v[22:23], v[24:25], v[34:35]
	s_waitcnt vmcnt(0)
	v_pk_mul_f32 v[32:33], v[46:47], v[36:37]
	v_pk_mul_f32 v[34:35], v[44:45], v[38:39]
	global_store_dwordx4 v[10:11], v[20:23], off
	global_store_dwordx4 v[10:11], v[32:35], off offset:16
	global_load_dwordx4 v[20:23], v[76:77], off
	s_nop 0
	global_load_dwordx4 v[32:35], v[76:77], off offset:16
	v_rsq_f32_e32 v24, v6
	v_lshl_add_u64 v[6:7], s[24:25], 0, v[96:97]
	v_lshl_add_u64 v[10:11], v[6:7], 0, v[74:75]
	v_mul_f32_e32 v25, 0x45800000, v24
	v_cndmask_b32_e32 v36, v24, v25, vcc
	v_pk_mul_f32 v[24:25], v[30:31], v[36:37] op_sel_hi:[1,0]
	v_pk_mul_f32 v[28:29], v[42:43], v[36:37] op_sel_hi:[1,0]
	v_pk_mul_f32 v[30:31], v[64:65], v[36:37] op_sel_hi:[1,0]
	v_pk_mul_f32 v[38:39], v[66:67], v[36:37] op_sel_hi:[1,0]
	v_pk_mul_f32 v[26:27], v[26:27], v[36:37] op_sel_hi:[1,0]
	v_pk_mul_f32 v[18:19], v[18:19], v[36:37] op_sel_hi:[1,0]
	v_pk_mul_f32 v[4:5], v[4:5], v[36:37] op_sel_hi:[1,0]
	v_pk_mul_f32 v[8:9], v[8:9], v[36:37] op_sel_hi:[1,0]
	s_waitcnt vmcnt(1)
	v_pk_mul_f32 v[20:21], v[20:21], v[28:29]
	v_pk_mul_f32 v[22:23], v[22:23], v[24:25]
	s_waitcnt vmcnt(0)
	v_pk_mul_f32 v[28:29], v[32:33], v[38:39]
	v_pk_mul_f32 v[30:31], v[34:35], v[30:31]
	global_store_dwordx4 v[10:11], v[20:23], off
	global_store_dwordx4 v[10:11], v[28:31], off offset:16
	global_load_dwordx4 v[20:23], v[76:77], off offset:2048
	s_nop 0
	global_load_dwordx4 v[28:31], v[76:77], off offset:2064
	v_pk_mul_f32 v[24:25], v[50:51], v[36:37] op_sel_hi:[1,0]
	v_pk_mul_f32 v[32:33], v[40:41], v[36:37] op_sel_hi:[1,0]
	v_pk_mul_f32 v[34:35], v[54:55], v[36:37] op_sel_hi:[1,0]
	s_waitcnt vmcnt(1)
	v_pk_mul_f32 v[20:21], v[20:21], v[26:27]
	v_pk_mul_f32 v[22:23], v[22:23], v[24:25]
	s_waitcnt vmcnt(0)
	v_pk_mul_f32 v[24:25], v[28:29], v[34:35]
	v_pk_mul_f32 v[26:27], v[30:31], v[32:33]
	global_store_dwordx4 v[10:11], v[20:23], off offset:2048
	global_store_dwordx4 v[10:11], v[24:27], off offset:2064
	global_load_dwordx4 v[20:23], v[78:79], off
	s_nop 0
	global_load_dwordx4 v[24:27], v[78:79], off offset:16
	v_pk_mul_f32 v[10:11], v[16:17], v[36:37] op_sel_hi:[1,0]
	v_lshl_add_u64 v[28:29], v[6:7], 0, v[86:87]
	v_pk_mul_f32 v[16:17], v[14:15], v[36:37] op_sel_hi:[1,0]
	v_pk_mul_f32 v[14:15], v[12:13], v[36:37] op_sel_hi:[1,0]
	s_waitcnt vmcnt(1)
	v_pk_mul_f32 v[10:11], v[20:21], v[10:11]
	v_pk_mul_f32 v[12:13], v[22:23], v[18:19]
	s_waitcnt vmcnt(0)
	v_pk_mul_f32 v[14:15], v[24:25], v[14:15]
	v_pk_mul_f32 v[16:17], v[26:27], v[16:17]
	global_store_dwordx4 v[28:29], v[10:13], off
	global_store_dwordx4 v[28:29], v[14:17], off offset:16
	global_load_dwordx4 v[10:13], v[80:81], off
	s_nop 0
	global_load_dwordx4 v[14:17], v[80:81], off offset:16
	v_lshl_add_u64 v[18:19], v[6:7], 0, v[88:89]
	v_add_u32_e32 v7, s9, v95
	v_cmp_lt_i32_e32 vcc, s15, v7
	v_add_u32_e32 v6, s74, v70
	s_or_b64 s[6:7], vcc, s[6:7]
	v_pk_mul_f32 v[20:21], v[2:3], v[36:37] op_sel_hi:[1,0]
	v_pk_mul_f32 v[22:23], v[0:1], v[36:37] op_sel_hi:[1,0]
	s_waitcnt vmcnt(1)
	v_pk_mul_f32 v[0:1], v[8:9], v[10:11]
	v_pk_mul_f32 v[2:3], v[4:5], v[12:13]
	s_waitcnt vmcnt(0)
	v_pk_mul_f32 v[8:9], v[22:23], v[14:15]
	v_pk_mul_f32 v[10:11], v[20:21], v[16:17]
	global_store_dwordx4 v[18:19], v[0:3], off
	global_store_dwordx4 v[18:19], v[8:11], off offset:16
	s_andn2_b64 exec, exec, s[6:7]
	s_cbranch_execz .LBB0_1197
.LBB0_1191:
	v_add_u32_e32 v2, s30, v95
	v_cmp_lt_i32_e32 vcc, s12, v2
	v_mov_b64_e32 v[98:99], v[70:71]
	v_mov_b64_e32 v[0:1], v[84:85]
	s_and_saveexec_b64 s[10:11], vcc
	v_add_u32_e32 v0, 0xffff8000, v70
	v_mov_b32_e32 v1, v75
	v_lshlrev_b64 v[0:1], 13, v[0:1]
	v_mov_b32_e32 v3, v75
	v_lshl_add_u64 v[0:1], s[38:39], 0, v[0:1]
	v_mov_b64_e32 v[98:99], v[2:3]
	s_or_b64 exec, exec, s[10:11]
	v_mad_u64_u32 v[4:5], s[10:11], v98, s13, v[82:83]
	v_mov_b32_e32 v8, v5
	v_lshl_add_u64 v[2:3], v[0:1], 0, v[74:75]
	v_mad_u64_u32 v[8:9], s[10:11], v99, s13, v[8:9]
	global_load_dwordx4 v[56:59], v[2:3], off offset:16 nt
	global_load_dwordx4 v[60:63], v[2:3], off nt
	v_mov_b32_e32 v5, v8
	global_load_dwordx4 v[44:47], v[2:3], off offset:2064 nt
	global_load_dwordx4 v[52:55], v[2:3], off offset:2048 nt
	global_load_dwordx4 v[64:67], v[4:5], off nt
	global_load_dwordx4 v[48:51], v[4:5], off offset:1024 nt
	v_lshl_add_u64 v[2:3], v[0:1], 0, v[90:91]
	v_lshl_add_u64 v[0:1], v[0:1], 0, v[92:93]
	global_load_dwordx4 v[32:35], v[2:3], off offset:16 nt
	global_load_dwordx4 v[36:39], v[2:3], off nt
	global_load_dwordx4 v[20:23], v[0:1], off offset:16 nt
	global_load_dwordx4 v[28:31], v[0:1], off nt
	global_load_dwordx4 v[40:43], v[4:5], off offset:2048 nt
	global_load_dwordx4 v[24:27], v[4:5], off offset:3072 nt
	v_cmp_lt_i32_e32 vcc, s12, v6
	s_and_saveexec_b64 s[10:11], vcc
	s_xor_b64 s[10:11], exec, s[10:11]
	v_add_u32_e32 v0, 0xffff8000, v6
	v_mov_b32_e32 v1, v75
	v_lshlrev_b64 v[0:1], 13, v[0:1]
	v_mov_b32_e32 v7, v75
	v_lshl_add_u64 v[0:1], s[38:39], 0, v[0:1]
	v_lshlrev_b64 v[96:97], 13, v[6:7]
	s_andn2_saveexec_b64 s[10:11], s[10:11]
	s_cbranch_execz .LBB0_1190
	v_ashrrev_i32_e32 v7, 31, v6
	v_lshlrev_b64 v[96:97], 13, v[6:7]
	v_lshl_add_u64 v[0:1], s[36:37], 0, v[96:97]
	s_branch .LBB0_1190

; __device__ __forceinline__ float bf_lo(unsigned w) { return __uint_as_float(w << 16); }
; __device__ __forceinline__ float bf_hi(unsigned w) { return __uint_as_float(w & 0xffff0000u); }
; template <int NR>
; __device__ __forceinline__ void p5_rows(const Params& p, const bf16_t* __restrict__ DL, int r, int nw, int lane) {
;     ...
; #pragma unroll
;     for (int k = 0; k < NR; ++k) { const int row = r + k * nw; const float* x = row < TP ? p.xp + (size_t)row * D : p.xs + (size_t)(row - TP) * D;
; #pragma unroll
;         for (int i = 0; i < 4; ++i) { v[k][2 * i] = *(const f32x4*)(x + (i * 64 + lane) * 8); v[k][2 * i + 1] = *(const f32x4*)(x + (i * 64 + lane) * 8 + 4);
;             d[k][i] = *(const u32x4*)(DL + (size_t)row * LDP + (i * 64 + lane) * 8); } }
; #pragma unroll
;     for (int k = 0; k < NR; ++k) { const int row = r + k * nw; float ss = 0.f;
; #pragma unroll
;         for (int i = 0; i < 4; ++i) { const u32x4 w = d[k][i];
;             v[k][2 * i] += (f32x4){bf_lo(w.x), bf_hi(w.x), bf_lo(w.y), bf_hi(w.y)}; v[k][2 * i + 1] += (f32x4){bf_lo(w.z), bf_hi(w.z), bf_lo(w.w), bf_hi(w.w)}; }
; #pragma unroll
;         for (int i = 0; i < 8; ++i) ss += (v[k][i][0] * v[k][i][0] + v[k][i][1] * v[k][i][1]) + (v[k][i][2] * v[k][i][2] + v[k][i][3] * v[k][i][3]);
; #pragma unroll
;         for (int o = 32; o >= 1; o >>= 1) ss += __shfl_xor(ss, o);
.LBB0_1198:
	s_or_b64 exec, exec, s[0:1]
	s_mov_b32 s0, 0x8800
	v_cmp_gt_i32_e32 vcc, s0, v70
	s_and_saveexec_b64 s[0:1], vcc
	s_cbranch_execz .LBB0_1200
	v_mov_b32_e32 v1, 0
	s_movk_i32 s0, 0x1080
	v_mov_b64_e32 v[2:3], s[26:27]
	v_mad_i64_i32 v[2:3], s[0:1], v70, s0, v[2:3]
	v_mov_b32_e32 v73, v1
	v_add_u32_e32 v0, 0xffff8000, v70
	v_ashrrev_i32_e32 v71, 31, v70
	v_lshl_add_u64 v[2:3], v[2:3], 0, v[72:73]
	s_mov_b32 s0, 0x8000
	v_lshlrev_b64 v[22:23], 13, v[0:1]
	v_lshlrev_b64 v[4:5], 13, v[70:71]
	global_load_dwordx4 v[6:9], v[2:3], off nt
	global_load_dwordx4 v[10:13], v[2:3], off offset:1024 nt
	global_load_dwordx4 v[14:17], v[2:3], off offset:2048 nt
	global_load_dwordx4 v[18:21], v[2:3], off offset:3072 nt
	v_lshl_add_u64 v[2:3], s[38:39], 0, v[22:23]
	v_lshl_add_u64 v[22:23], s[36:37], 0, v[4:5]
	v_cmp_gt_i32_e32 vcc, s0, v70
	v_mov_b32_e32 v69, v1
	v_or_b32_e32 v0, 0x1000, v68
	v_cndmask_b32_e32 v47, v3, v23, vcc
	v_cndmask_b32_e32 v46, v2, v22, vcc
	v_lshl_add_u64 v[2:3], v[46:47], 0, v[68:69]
	global_load_dwordx4 v[22:25], v[2:3], off nt
	global_load_dwordx4 v[26:29], v[2:3], off offset:16 nt
	global_load_dwordx4 v[30:33], v[2:3], off offset:2064 nt
	global_load_dwordx4 v[34:37], v[2:3], off offset:2048 nt
	v_lshl_add_u64 v[2:3], v[46:47], 0, v[0:1]
	global_load_dwordx4 v[38:41], v[2:3], off offset:16 nt
	global_load_dwordx4 v[42:45], v[2:3], off nt
	v_or_b32_e32 v2, 0x1800, v68
	v_mov_b32_e32 v3, v1
	v_lshl_add_u64 v[54:55], v[46:47], 0, v[2:3]
	global_load_dwordx4 v[46:49], v[54:55], off nt
	global_load_dwordx4 v[50:53], v[54:55], off offset:16 nt
	v_mbcnt_hi_u32_b32 v74, -1, v190
	v_and_b32_e32 v54, 64, v74
	v_add_u32_e32 v75, 64, v54
	s_mov_b32 s0, 0x800000
	v_lshl_add_u64 v[4:5], s[24:25], 0, v[4:5]
	s_waitcnt vmcnt(11)
	v_lshlrev_b32_e32 v54, 16, v6
	v_and_b32_e32 v55, 0xffff0000, v6
	v_lshlrev_b32_e32 v56, 16, v8
	v_and_b32_e32 v57, 0xffff0000, v8
	v_lshlrev_b32_e32 v6, 16, v7
	v_and_b32_e32 v7, 0xffff0000, v7
	v_lshlrev_b32_e32 v8, 16, v9
	v_and_b32_e32 v9, 0xffff0000, v9
	s_waitcnt vmcnt(8)
	v_lshlrev_b32_e32 v70, 16, v20
	v_and_b32_e32 v71, 0xffff0000, v20
	v_lshlrev_b32_e32 v20, 16, v21
	v_and_b32_e32 v21, 0xffff0000, v21
	s_waitcnt vmcnt(7)
	v_pk_add_f32 v[54:55], v[22:23], v[54:55]
	s_waitcnt vmcnt(6)
	v_pk_add_f32 v[26:27], v[26:27], v[56:57]
	v_lshlrev_b32_e32 v66, 16, v18
	v_and_b32_e32 v67, 0xffff0000, v18
	v_lshlrev_b32_e32 v18, 16, v19
	v_and_b32_e32 v19, 0xffff0000, v19
	v_pk_add_f32 v[72:73], v[24:25], v[6:7]
	v_pk_add_f32 v[28:29], v[28:29], v[8:9]
	s_waitcnt vmcnt(0)
	v_pk_add_f32 v[6:7], v[52:53], v[20:21]
	v_mov_b32_e32 v20, v55
	v_mov_b32_e32 v21, v27
	v_pk_add_f32 v[8:9], v[48:49], v[18:19]
	v_mov_b32_e32 v18, v54
	v_mov_b32_e32 v19, v26
	v_pk_mul_f32 v[20:21], v[20:21], v[20:21]
	v_mov_b32_e32 v22, v73
	v_mov_b32_e32 v23, v29
	v_lshlrev_b32_e32 v58, 16, v10
	v_and_b32_e32 v59, 0xffff0000, v10
	v_lshlrev_b32_e32 v10, 16, v11
	v_and_b32_e32 v11, 0xffff0000, v11
	v_pk_fma_f32 v[18:19], v[18:19], v[18:19], v[20:21]
	v_mov_b32_e32 v20, v72
	v_mov_b32_e32 v21, v28
	v_pk_mul_f32 v[22:23], v[22:23], v[22:23]
	v_pk_add_f32 v[36:37], v[36:37], v[10:11]
	v_pk_add_f32 v[34:35], v[34:35], v[58:59]
	v_pk_fma_f32 v[20:21], v[20:21], v[20:21], v[22:23]
	v_lshlrev_b32_e32 v60, 16, v12
	v_and_b32_e32 v61, 0xffff0000, v12
	v_pk_add_f32 v[18:19], v[18:19], v[20:21]
	v_pk_mul_f32 v[20:21], v[36:37], v[36:37]
	v_pk_mul_f32 v[22:23], v[34:35], v[34:35]
	v_lshlrev_b32_e32 v62, 16, v14
	v_and_b32_e32 v63, 0xffff0000, v14
	v_pk_add_f32 v[30:31], v[30:31], v[60:61]
	v_pk_mov_b32 v[24:25], v[22:23], v[20:21] op_sel:[1,0]
	v_mov_b32_e32 v23, v21
	v_lshlrev_b32_e32 v12, 16, v13
	v_and_b32_e32 v13, 0xffff0000, v13
	v_pk_add_f32 v[42:43], v[42:43], v[62:63]
	v_pk_add_f32 v[20:21], v[24:25], v[22:23]
	v_mul_f32_e32 v22, v31, v31
	v_lshlrev_b32_e32 v14, 16, v15
	v_and_b32_e32 v15, 0xffff0000, v15
	v_pk_add_f32 v[32:33], v[32:33], v[12:13]
	v_mul_f32_e32 v24, v42, v42
	v_pk_fma_f32 v[22:23], v[30:31], v[30:31], v[22:23] op_sel_hi:[1,1,0]
	v_lshlrev_b32_e32 v64, 16, v16
	v_and_b32_e32 v65, 0xffff0000, v16
	v_lshlrev_b32_e32 v16, 16, v17
	v_and_b32_e32 v17, 0xffff0000, v17
	v_pk_add_f32 v[44:45], v[44:45], v[14:15]
	v_mov_b32_e32 v23, v24
	v_mul_f32_e32 v24, v33, v33
	v_pk_add_f32 v[14:15], v[40:41], v[16:17]
	v_pk_add_f32 v[16:17], v[38:39], v[64:65]
	v_mul_f32_e32 v38, v43, v43
	v_mul_f32_e32 v39, v44, v44
	v_mul_f32_e32 v40, v45, v45
	v_pk_fma_f32 v[24:25], v[32:33], v[32:33], v[24:25] op_sel_hi:[1,1,0]
	v_pk_add_f32 v[18:19], v[18:19], v[18:19] op_sel:[0,1] op_sel_hi:[1,0]
	v_pk_add_f32 v[20:21], v[20:21], v[20:21] op_sel:[0,1] op_sel_hi:[1,0]
	v_mov_b32_e32 v25, v38
	v_mov_b32_e32 v19, v39
	v_mov_b32_e32 v21, v40
	v_pk_add_f32 v[22:23], v[22:23], v[24:25]
	v_pk_add_f32 v[18:19], v[18:19], v[20:21]
	v_pk_mul_f32 v[20:21], v[16:17], v[16:17]
	v_pk_add_f32 v[18:19], v[22:23], v[18:19]
	v_pk_add_f32 v[10:11], v[46:47], v[66:67]
	v_pk_add_f32 v[38:39], v[18:19], v[18:19] op_sel_hi:[0,1]
	v_pk_mul_f32 v[18:19], v[14:15], v[14:15]
	v_pk_add_f32 v[12:13], v[50:51], v[70:71]
	v_pk_mov_b32 v[22:23], v[20:21], v[18:19] op_sel:[1,0]
	v_mov_b32_e32 v21, v19
	v_pk_add_f32 v[18:19], v[22:23], v[20:21]
	v_mul_f32_e32 v38, v13, v13
	v_pk_add_f32 v[40:41], v[18:19], v[18:19] op_sel_hi:[0,1]
	v_mul_f32_e32 v18, v10, v10
	v_pk_fma_f32 v[46:47], v[10:11], v[10:11], v[18:19] op_sel_hi:[1,1,0]
	v_mul_f32_e32 v18, v8, v8
	v_pk_fma_f32 v[48:49], v[8:9], v[8:9], v[18:19] op_sel_hi:[1,1,0]
	global_load_dwordx4 v[18:21], v68, s[22:23] offset:16
	global_load_dwordx4 v[22:25], v68, s[22:23]
	v_mul_f32_e32 v40, v12, v12
	v_mul_f32_e32 v46, v6, v6
	v_mul_f32_e32 v48, v7, v7
	v_pk_add_f32 v[38:39], v[40:41], v[38:39]
	v_pk_add_f32 v[40:41], v[46:47], v[48:49]
	s_nop 0
	v_pk_add_f32 v[38:39], v[38:39], v[40:41]
	s_nop 0
	v_add_f32_e32 v38, v38, v39
	v_xor_b32_e32 v39, 32, v74
	v_cmp_lt_i32_e32 vcc, v39, v75
	s_nop 1
	v_cndmask_b32_e32 v39, v74, v39, vcc
	v_lshlrev_b32_e32 v39, 2, v39
	ds_bpermute_b32 v39, v39, v38
	s_waitcnt lgkmcnt(0)
; template <int NR>
; __device__ __forceinline__ void p5_rows(const Params& p, const bf16_t* __restrict__ DL, int r, int nw, int lane) {
;     ...
;         for (int o = 32; o >= 1; o >>= 1) ss += __shfl_xor(ss, o);
;         const float rs = rsqrtf(ss * (1.0f / D) + EPS);
;         float* y = p.out + O_Y + (size_t)row * D;
; #pragma unroll
;         for (int i = 0; i < 4; ++i) { const f32x4 g0 = *(const f32x4*)(p.fng + (i * 64 + lane) * 8), g1 = *(const f32x4*)(p.fng + (i * 64 + lane) * 8 + 4);
;             *(f32x4*)(y + (i * 64 + lane) * 8) = v[k][2 * i] * rs * g0; *(f32x4*)(y + (i * 64 + lane) * 8 + 4) = v[k][2 * i + 1] * rs * g1; } }
	v_add_f32_e32 v38, v38, v39
	v_xor_b32_e32 v39, 16, v74
	v_cmp_lt_i32_e32 vcc, v39, v75
	s_nop 1
	v_cndmask_b32_e32 v39, v74, v39, vcc
	v_lshlrev_b32_e32 v39, 2, v39
	ds_bpermute_b32 v39, v39, v38
	s_waitcnt lgkmcnt(0)
	v_add_f32_e32 v38, v38, v39
	v_xor_b32_e32 v39, 8, v74
	v_cmp_lt_i32_e32 vcc, v39, v75
	s_nop 1
	v_cndmask_b32_e32 v39, v74, v39, vcc
	v_lshlrev_b32_e32 v39, 2, v39
	ds_bpermute_b32 v39, v39, v38
	s_waitcnt lgkmcnt(0)
	v_add_f32_e32 v38, v38, v39
	v_xor_b32_e32 v39, 4, v74
	v_cmp_lt_i32_e32 vcc, v39, v75
	s_nop 1
	v_cndmask_b32_e32 v39, v74, v39, vcc
	v_lshlrev_b32_e32 v39, 2, v39
	ds_bpermute_b32 v39, v39, v38
	s_waitcnt lgkmcnt(0)
	v_add_f32_e32 v38, v38, v39
	v_xor_b32_e32 v39, 2, v74
	v_cmp_lt_i32_e32 vcc, v39, v75
	s_nop 1
	v_cndmask_b32_e32 v39, v74, v39, vcc
	v_lshlrev_b32_e32 v39, 2, v39
	ds_bpermute_b32 v39, v39, v38
	s_waitcnt lgkmcnt(0)
	v_add_f32_e32 v38, v38, v39
	v_xor_b32_e32 v39, 1, v74
	v_cmp_lt_i32_e32 vcc, v39, v75
	s_nop 1
	v_cndmask_b32_e32 v39, v74, v39, vcc
	v_lshlrev_b32_e32 v39, 2, v39
	ds_bpermute_b32 v39, v39, v38
	s_waitcnt lgkmcnt(0)
	v_add_f32_e32 v38, v38, v39
	v_mov_b32_e32 v39, 0x358637bd
	v_fmac_f32_e32 v39, 0x3a000000, v38
	v_mul_f32_e32 v38, 0x4b800000, v39
	v_cmp_gt_f32_e32 vcc, s0, v39
	s_nop 1
	v_cndmask_b32_e32 v38, v39, v38, vcc
	v_rsq_f32_e32 v38, v38
	s_nop 0
	v_mul_f32_e32 v39, 0x45800000, v38
	v_cndmask_b32_e32 v38, v38, v39, vcc
	v_pk_mul_f32 v[40:41], v[54:55], v[38:39] op_sel_hi:[1,0]
	v_pk_mul_f32 v[46:47], v[72:73], v[38:39] op_sel_hi:[1,0]
	s_waitcnt vmcnt(0)
	v_pk_mul_f32 v[22:23], v[22:23], v[40:41]
	v_pk_mul_f32 v[24:25], v[24:25], v[46:47]
	v_lshl_add_u64 v[40:41], v[4:5], 0, v[68:69]
	global_store_dwordx4 v[40:41], v[22:25], off
	v_pk_mul_f32 v[32:33], v[32:33], v[38:39] op_sel_hi:[1,0]
	v_pk_mul_f32 v[30:31], v[30:31], v[38:39] op_sel_hi:[1,0]
	v_pk_mul_f32 v[22:23], v[26:27], v[38:39] op_sel_hi:[1,0]
	v_pk_mul_f32 v[24:25], v[28:29], v[38:39] op_sel_hi:[1,0]
	v_pk_mul_f32 v[18:19], v[18:19], v[22:23]
	v_pk_mul_f32 v[20:21], v[20:21], v[24:25]
	global_store_dwordx4 v[40:41], v[18:21], off offset:16
	global_load_dwordx4 v[18:21], v68, s[22:23] offset:2048
	s_nop 0
	global_load_dwordx4 v[22:25], v68, s[22:23] offset:2064
	v_pk_mul_f32 v[26:27], v[36:37], v[38:39] op_sel_hi:[1,0]
	v_pk_mul_f32 v[28:29], v[34:35], v[38:39] op_sel_hi:[1,0]
	v_pk_mul_f32 v[6:7], v[6:7], v[38:39] op_sel_hi:[1,0]
	s_waitcnt vmcnt(1)
	v_pk_mul_f32 v[18:19], v[18:19], v[28:29]
	v_pk_mul_f32 v[20:21], v[20:21], v[26:27]
	s_waitcnt vmcnt(0)
	v_pk_mul_f32 v[22:23], v[22:23], v[30:31]
	v_pk_mul_f32 v[24:25], v[24:25], v[32:33]
	global_store_dwordx4 v[40:41], v[18:21], off offset:2048
	global_store_dwordx4 v[40:41], v[22:25], off offset:2064
	global_load_dwordx4 v[18:21], v0, s[22:23]
	s_nop 0
	global_load_dwordx4 v[22:25], v0, s[22:23] offset:16
	v_pk_mul_f32 v[26:27], v[44:45], v[38:39] op_sel_hi:[1,0]
	v_pk_mul_f32 v[28:29], v[42:43], v[38:39] op_sel_hi:[1,0]
	v_lshl_add_u64 v[0:1], v[4:5], 0, v[0:1]
	v_pk_mul_f32 v[30:31], v[14:15], v[38:39] op_sel_hi:[1,0]
	v_pk_mul_f32 v[32:33], v[16:17], v[38:39] op_sel_hi:[1,0]
	s_waitcnt vmcnt(1)
	v_pk_mul_f32 v[14:15], v[18:19], v[28:29]
	v_pk_mul_f32 v[16:17], v[20:21], v[26:27]
	s_waitcnt vmcnt(0)
	v_pk_mul_f32 v[18:19], v[22:23], v[32:33]
	v_pk_mul_f32 v[20:21], v[24:25], v[30:31]
	global_store_dwordx4 v[0:1], v[14:17], off
	global_store_dwordx4 v[0:1], v[18:21], off offset:16
	global_load_dwordx4 v[14:17], v2, s[22:23]
	s_nop 0
	global_load_dwordx4 v[18:21], v2, s[22:23] offset:16
	v_lshl_add_u64 v[22:23], v[4:5], 0, v[2:3]
	v_pk_mul_f32 v[2:3], v[8:9], v[38:39] op_sel_hi:[1,0]
	v_pk_mul_f32 v[0:1], v[10:11], v[38:39] op_sel_hi:[1,0]
	v_pk_mul_f32 v[4:5], v[12:13], v[38:39] op_sel_hi:[1,0]
	s_waitcnt vmcnt(1)
	v_pk_mul_f32 v[0:1], v[14:15], v[0:1]
	v_pk_mul_f32 v[2:3], v[16:17], v[2:3]
	s_waitcnt vmcnt(0)
	v_pk_mul_f32 v[4:5], v[18:19], v[4:5]
	v_pk_mul_f32 v[6:7], v[20:21], v[6:7]
	global_store_dwordx4 v[22:23], v[0:3], off
	global_store_dwordx4 v[22:23], v[4:7], off offset:16
